# rwkv_pre_wave low-rank projections: all six loads of a k-step issued 3 steps ahead into register rings (was 4 serialized load round trips per step, 64 per item)
# speedup vs baseline: 1.0013x; 1.0013x over previous
.LBB0_800:
	s_mul_hi_i32 s0, s66, 0x7e07e07f
	s_lshr_b32 s1, s0, 31
	s_ashr_i32 s8, s0, 5
	s_add_i32 s8, s8, s1
	s_mul_i32 s0, s8, 0x41
	s_sub_i32 s12, s66, s0
	s_ashr_i32 s13, s8, 3
	s_lshl_b32 s10, s12, 5
	s_cmp_lg_u32 s12, 64
	v_and_b32_e32 v107, 31, v136
	s_cselect_b64 s[0:1], -1, 0
	v_or_b32_e32 v4, s10, v107
	v_cmp_gt_u32_e32 vcc, 16, v107
	v_ashrrev_i32_e32 v0, 31, v4
	s_or_b64 s[2:3], s[0:1], vcc
	v_cndmask_b32_e64 v1, 0, v0, s[2:3]
	v_cndmask_b32_e64 v0, 0, v4, s[2:3]
	v_mov_b32_e32 v2, 0x810
	v_ashrrev_i32_e32 v138, 5, v136
	v_mad_i64_i32 v[0:1], s[4:5], s13, v2, v[0:1]
	v_mov_b64_e32 v[2:3], s[56:57]
	v_mad_u64_u32 v[2:3], s[4:5], v0, s44, v[2:3]
	v_lshlrev_b32_e32 v68, 3, v138
	v_mad_i32_i24 v3, v1, s44, v3
	v_ashrrev_i32_e32 v69, 31, v68
	v_lshl_add_u64 v[102:103], v[68:69], 1, v[2:3]
	v_cmp_lt_i32_e64 s[4:5], 0, v4
	s_and_b32 s14, s8, 7
	s_lshl_b32 s11, s14, 6
	s_mul_hi_i32 s7, s13, 0x810
	s_mul_i32 s6, s13, 0x810
	v_or_b32_e32 v134, s34, v107
	v_or_b32_e32 v134, s11, v134
	v_mov_b32_e32 v135, s35
	v_lshlrev_b64 v[110:111], 7, v[134:135]
	v_lshlrev_b64 v[114:115], 8, v[134:135]
	v_lshl_add_u64 v[110:111], s[92:93], 0, v[110:111]
	v_lshl_add_u64 v[114:115], s[92:93], 0, v[114:115]
	v_lshl_add_u64 v[110:111], v[68:69], 1, v[110:111]
	v_lshl_add_u64 v[114:115], v[68:69], 1, v[114:115]
	s_mov_b64 s[100:101], 0x800
	v_lshl_add_u64 v[110:111], v[110:111], 0, s[100:101]
	s_mov_b64 s[100:101], 0x40000
	v_lshl_add_u64 v[112:113], v[110:111], 0, s[100:101]
	s_mov_b64 s[100:101], 0x80000
	v_lshl_add_u64 v[114:115], v[114:115], 0, s[100:101]
	s_mov_b64 s[100:101], 0x2000
	v_lshl_add_u64 v[116:117], v[114:115], 0, s[100:101]
	v_lshl_add_u64 v[108:109], v[68:69], 2, s[60:61]
	s_mov_b64 s[100:101], 0x1800
	v_lshl_add_u64 v[108:109], v[108:109], 0, s[100:101]
	s_mov_b32 s100, 0xffffdc00
	s_mov_b32 s101, -1
	v_lshl_add_u64 v[104:105], v[102:103], 0, s[100:101]
	s_mov_b64 s[100:101], 0xc00
	v_lshl_add_u64 v[134:135], v[102:103], 0, s[100:101]
	v_cndmask_b32_e64 v104, v134, v104, s[4:5]
	v_cndmask_b32_e64 v105, v135, v105, s[4:5]
	global_load_dwordx4 v[192:195], v[110:111], off offset:-2048
	global_load_dwordx4 v[196:199], v[110:111], off offset:2048
	global_load_dwordx4 v[144:147], v[102:103], off offset:3072
	global_load_dwordx4 v[148:151], v[104:105], off
	global_load_dwordx4 v[152:155], v[108:109], off
	global_load_dwordx4 v[156:159], v[108:109], off offset:16
	global_load_dword v212, v[102:103], off offset:3200
	global_load_dword v213, v[102:103], off offset:3328
	global_load_dword v214, v[102:103], off offset:3456
	global_load_dword v139, v[104:105], off offset:128
	global_load_dword v244, v[104:105], off offset:256
	global_load_dword v245, v[104:105], off offset:384
	global_load_dwordx4 v[200:203], v[110:111], off offset:-2016
	global_load_dwordx4 v[204:207], v[110:111], off offset:2080
	global_load_dwordx4 v[160:163], v[102:103], off offset:3104
	global_load_dwordx4 v[164:167], v[104:105], off offset:32
	global_load_dwordx4 v[168:171], v[108:109], off offset:64
	global_load_dwordx4 v[172:175], v[108:109], off offset:80
	global_load_dwordx4 v[208:211], v[110:111], off offset:-1984
	global_load_dwordx4 v[222:225], v[110:111], off offset:2112
	global_load_dwordx4 v[176:179], v[102:103], off offset:3136
	global_load_dwordx4 v[180:183], v[104:105], off offset:64
	global_load_dwordx4 v[184:187], v[108:109], off offset:128
	global_load_dwordx4 v[188:191], v[108:109], off offset:144
	global_load_dwordx4 v[226:229], v[110:111], off offset:-1952
	global_load_dwordx4 v[238:241], v[110:111], off offset:2144
	s_waitcnt vmcnt(20)
	v_lshlrev_b32_e32 v118, 16, v144
	v_and_b32_e32 v119, 0xffff0000, v144
	v_lshlrev_b32_e32 v120, 16, v145
	v_and_b32_e32 v121, 0xffff0000, v145
	v_lshlrev_b32_e32 v122, 16, v146
	v_and_b32_e32 v123, 0xffff0000, v146
	v_lshlrev_b32_e32 v124, 16, v147
	v_and_b32_e32 v125, 0xffff0000, v147
	v_cndmask_b32_e64 v148, 0, v148, s[4:5]
	v_cndmask_b32_e64 v149, 0, v149, s[4:5]
	v_cndmask_b32_e64 v150, 0, v150, s[4:5]
	v_cndmask_b32_e64 v151, 0, v151, s[4:5]
	v_lshlrev_b32_e32 v126, 16, v148
	v_and_b32_e32 v127, 0xffff0000, v148
	v_lshlrev_b32_e32 v128, 16, v149
	v_and_b32_e32 v129, 0xffff0000, v149
	v_lshlrev_b32_e32 v130, 16, v150
	v_and_b32_e32 v131, 0xffff0000, v150
	v_lshlrev_b32_e32 v132, 16, v151
	v_and_b32_e32 v133, 0xffff0000, v151
	global_load_dwordx4 v[144:147], v[102:103], off offset:3168
	global_load_dwordx4 v[148:151], v[104:105], off offset:96
	v_sub_f32_e32 v126, v126, v118
	v_sub_f32_e32 v127, v127, v119
	v_sub_f32_e32 v128, v128, v120
	v_sub_f32_e32 v129, v129, v121
	v_sub_f32_e32 v130, v130, v122
	v_sub_f32_e32 v131, v131, v123
	v_sub_f32_e32 v132, v132, v124
	v_sub_f32_e32 v133, v133, v125
	v_fmac_f32_e32 v118, v126, v152
	v_fmac_f32_e32 v119, v127, v153
	v_fmac_f32_e32 v120, v128, v154
	v_fmac_f32_e32 v121, v129, v155
	v_fmac_f32_e32 v122, v130, v156
	v_fmac_f32_e32 v123, v131, v157
	v_fmac_f32_e32 v124, v132, v158
	v_fmac_f32_e32 v125, v133, v159
	global_load_dwordx4 v[152:155], v[108:109], off offset:192
	global_load_dwordx4 v[156:159], v[108:109], off offset:208
	v_add_f32_e32 v126, v118, v118
	v_add_f32_e32 v127, v119, v119
	v_add_f32_e32 v128, v120, v120
	v_add_f32_e32 v129, v121, v121
	v_add_f32_e32 v130, v122, v122
	v_add_f32_e32 v131, v123, v123
	v_add_f32_e32 v132, v124, v124
	v_add_f32_e32 v133, v125, v125
	v_mul_f32_e32 v126, 0x3fb8aa3b, v126
	v_mul_f32_e32 v127, 0x3fb8aa3b, v127
	v_mul_f32_e32 v128, 0x3fb8aa3b, v128
	v_mul_f32_e32 v129, 0x3fb8aa3b, v129
	v_mul_f32_e32 v130, 0x3fb8aa3b, v130
	v_mul_f32_e32 v131, 0x3fb8aa3b, v131
	v_mul_f32_e32 v132, 0x3fb8aa3b, v132
	v_mul_f32_e32 v133, 0x3fb8aa3b, v133
	v_exp_f32_e32 v126, v126
	v_exp_f32_e32 v127, v127
	v_exp_f32_e32 v128, v128
	v_exp_f32_e32 v129, v129
	v_exp_f32_e32 v130, v130
	v_exp_f32_e32 v131, v131
	v_exp_f32_e32 v132, v132
	v_exp_f32_e32 v133, v133
	v_add_f32_e32 v126, 1.0, v126
	v_add_f32_e32 v127, 1.0, v127
	v_add_f32_e32 v128, 1.0, v128
	v_add_f32_e32 v129, 1.0, v129
	v_add_f32_e32 v130, 1.0, v130
	v_add_f32_e32 v131, 1.0, v131
	v_add_f32_e32 v132, 1.0, v132
	v_add_f32_e32 v133, 1.0, v133
	v_rcp_f32_e32 v126, v126
	v_rcp_f32_e32 v127, v127
	v_rcp_f32_e32 v128, v128
	v_rcp_f32_e32 v129, v129
	v_rcp_f32_e32 v130, v130
	v_rcp_f32_e32 v131, v131
	v_rcp_f32_e32 v132, v132
	v_rcp_f32_e32 v133, v133
	v_fma_f32 v118, v126, -2.0, 1.0
	v_fma_f32 v119, v127, -2.0, 1.0
	v_fma_f32 v120, v128, -2.0, 1.0
	v_fma_f32 v121, v129, -2.0, 1.0
	v_fma_f32 v122, v130, -2.0, 1.0
	v_fma_f32 v123, v131, -2.0, 1.0
	v_fma_f32 v124, v132, -2.0, 1.0
	v_fma_f32 v125, v133, -2.0, 1.0
	s_nop 0
	v_cvt_pk_bf16_f32 v98, v118, v119
	v_cvt_pk_bf16_f32 v99, v120, v121
	v_cvt_pk_bf16_f32 v100, v122, v123
	v_cvt_pk_bf16_f32 v101, v124, v125
	v_cndmask_b32_e64 v98, 0, v98, s[2:3]
	v_cndmask_b32_e64 v99, 0, v99, s[2:3]
	v_cndmask_b32_e64 v100, 0, v100, s[2:3]
	v_cndmask_b32_e64 v101, 0, v101, s[2:3]
	s_nop 1
	v_mfma_f32_32x32x16_bf16 v[32:47], v[98:101], v[192:195], 0
	v_mfma_f32_32x32x16_bf16 v[48:63], v[98:101], v[196:199], 0
	global_load_dwordx4 v[192:195], v[112:113], off offset:-2048
	global_load_dwordx4 v[196:199], v[112:113], off offset:2048
	s_waitcnt vmcnt(14)
	v_lshlrev_b32_e32 v118, 16, v160
	v_and_b32_e32 v119, 0xffff0000, v160
	v_lshlrev_b32_e32 v120, 16, v161
	v_and_b32_e32 v121, 0xffff0000, v161
	v_lshlrev_b32_e32 v122, 16, v162
	v_and_b32_e32 v123, 0xffff0000, v162
	v_lshlrev_b32_e32 v124, 16, v163
	v_and_b32_e32 v125, 0xffff0000, v163
	v_cndmask_b32_e64 v164, 0, v164, s[4:5]
	v_cndmask_b32_e64 v165, 0, v165, s[4:5]
	v_cndmask_b32_e64 v166, 0, v166, s[4:5]
	v_cndmask_b32_e64 v167, 0, v167, s[4:5]
	v_lshlrev_b32_e32 v126, 16, v164
	v_and_b32_e32 v127, 0xffff0000, v164
	v_lshlrev_b32_e32 v128, 16, v165
	v_and_b32_e32 v129, 0xffff0000, v165
	v_lshlrev_b32_e32 v130, 16, v166
	v_and_b32_e32 v131, 0xffff0000, v166
	v_lshlrev_b32_e32 v132, 16, v167
	v_and_b32_e32 v133, 0xffff0000, v167
	global_load_dwordx4 v[160:163], v[102:103], off offset:3200
	global_load_dwordx4 v[164:167], v[104:105], off offset:128
	v_sub_f32_e32 v126, v126, v118
	v_sub_f32_e32 v127, v127, v119
	v_sub_f32_e32 v128, v128, v120
	v_sub_f32_e32 v129, v129, v121
	v_sub_f32_e32 v130, v130, v122
	v_sub_f32_e32 v131, v131, v123
	v_sub_f32_e32 v132, v132, v124
	v_sub_f32_e32 v133, v133, v125
	v_fmac_f32_e32 v118, v126, v168
	v_fmac_f32_e32 v119, v127, v169
	v_fmac_f32_e32 v120, v128, v170
	v_fmac_f32_e32 v121, v129, v171
	v_fmac_f32_e32 v122, v130, v172
	v_fmac_f32_e32 v123, v131, v173
	v_fmac_f32_e32 v124, v132, v174
	v_fmac_f32_e32 v125, v133, v175
	global_load_dwordx4 v[168:171], v[108:109], off offset:256
	global_load_dwordx4 v[172:175], v[108:109], off offset:272
	v_add_f32_e32 v126, v118, v118
	v_add_f32_e32 v127, v119, v119
	v_add_f32_e32 v128, v120, v120
	v_add_f32_e32 v129, v121, v121
	v_add_f32_e32 v130, v122, v122
	v_add_f32_e32 v131, v123, v123
	v_add_f32_e32 v132, v124, v124
	v_add_f32_e32 v133, v125, v125
	v_mul_f32_e32 v126, 0x3fb8aa3b, v126
	v_mul_f32_e32 v127, 0x3fb8aa3b, v127
	v_mul_f32_e32 v128, 0x3fb8aa3b, v128
	v_mul_f32_e32 v129, 0x3fb8aa3b, v129
	v_mul_f32_e32 v130, 0x3fb8aa3b, v130
	v_mul_f32_e32 v131, 0x3fb8aa3b, v131
	v_mul_f32_e32 v132, 0x3fb8aa3b, v132
	v_mul_f32_e32 v133, 0x3fb8aa3b, v133
	v_exp_f32_e32 v126, v126
	v_exp_f32_e32 v127, v127
	v_exp_f32_e32 v128, v128
	v_exp_f32_e32 v129, v129
	v_exp_f32_e32 v130, v130
	v_exp_f32_e32 v131, v131
	v_exp_f32_e32 v132, v132
	v_exp_f32_e32 v133, v133
	v_add_f32_e32 v126, 1.0, v126
	v_add_f32_e32 v127, 1.0, v127
	v_add_f32_e32 v128, 1.0, v128
	v_add_f32_e32 v129, 1.0, v129
	v_add_f32_e32 v130, 1.0, v130
	v_add_f32_e32 v131, 1.0, v131
	v_add_f32_e32 v132, 1.0, v132
	v_add_f32_e32 v133, 1.0, v133
	v_rcp_f32_e32 v126, v126
	v_rcp_f32_e32 v127, v127
	v_rcp_f32_e32 v128, v128
	v_rcp_f32_e32 v129, v129
	v_rcp_f32_e32 v130, v130
	v_rcp_f32_e32 v131, v131
	v_rcp_f32_e32 v132, v132
	v_rcp_f32_e32 v133, v133
	v_fma_f32 v118, v126, -2.0, 1.0
	v_fma_f32 v119, v127, -2.0, 1.0
	v_fma_f32 v120, v128, -2.0, 1.0
	v_fma_f32 v121, v129, -2.0, 1.0
	v_fma_f32 v122, v130, -2.0, 1.0
	v_fma_f32 v123, v131, -2.0, 1.0
	v_fma_f32 v124, v132, -2.0, 1.0
	v_fma_f32 v125, v133, -2.0, 1.0
	s_nop 0
	v_cvt_pk_bf16_f32 v98, v118, v119
	v_cvt_pk_bf16_f32 v99, v120, v121
	v_cvt_pk_bf16_f32 v100, v122, v123
	v_cvt_pk_bf16_f32 v101, v124, v125
	v_cndmask_b32_e64 v98, 0, v98, s[2:3]
	v_cndmask_b32_e64 v99, 0, v99, s[2:3]
	v_cndmask_b32_e64 v100, 0, v100, s[2:3]
	v_cndmask_b32_e64 v101, 0, v101, s[2:3]
	s_nop 1
	v_mfma_f32_32x32x16_bf16 v[32:47], v[98:101], v[200:203], v[32:47]
	v_mfma_f32_32x32x16_bf16 v[48:63], v[98:101], v[204:207], v[48:63]
	global_load_dwordx4 v[200:203], v[112:113], off offset:-2016
	global_load_dwordx4 v[204:207], v[112:113], off offset:2080
	s_waitcnt vmcnt(14)
	v_lshlrev_b32_e32 v118, 16, v176
	v_and_b32_e32 v119, 0xffff0000, v176
	v_lshlrev_b32_e32 v120, 16, v177
	v_and_b32_e32 v121, 0xffff0000, v177
	v_lshlrev_b32_e32 v122, 16, v178
	v_and_b32_e32 v123, 0xffff0000, v178
	v_lshlrev_b32_e32 v124, 16, v179
	v_and_b32_e32 v125, 0xffff0000, v179
	v_cndmask_b32_e64 v180, 0, v180, s[4:5]
	v_cndmask_b32_e64 v181, 0, v181, s[4:5]
	v_cndmask_b32_e64 v182, 0, v182, s[4:5]
	v_cndmask_b32_e64 v183, 0, v183, s[4:5]
	v_lshlrev_b32_e32 v126, 16, v180
	v_and_b32_e32 v127, 0xffff0000, v180
	v_lshlrev_b32_e32 v128, 16, v181
	v_and_b32_e32 v129, 0xffff0000, v181
	v_lshlrev_b32_e32 v130, 16, v182
	v_and_b32_e32 v131, 0xffff0000, v182
	v_lshlrev_b32_e32 v132, 16, v183
	v_and_b32_e32 v133, 0xffff0000, v183
	global_load_dwordx4 v[176:179], v[102:103], off offset:3232
	global_load_dwordx4 v[180:183], v[104:105], off offset:160
	v_sub_f32_e32 v126, v126, v118
	v_sub_f32_e32 v127, v127, v119
	v_sub_f32_e32 v128, v128, v120
	v_sub_f32_e32 v129, v129, v121
	v_sub_f32_e32 v130, v130, v122
	v_sub_f32_e32 v131, v131, v123
	v_sub_f32_e32 v132, v132, v124
	v_sub_f32_e32 v133, v133, v125
	v_fmac_f32_e32 v118, v126, v184
	v_fmac_f32_e32 v119, v127, v185
	v_fmac_f32_e32 v120, v128, v186
	v_fmac_f32_e32 v121, v129, v187
	v_fmac_f32_e32 v122, v130, v188
	v_fmac_f32_e32 v123, v131, v189
	v_fmac_f32_e32 v124, v132, v190
	v_fmac_f32_e32 v125, v133, v191
	global_load_dwordx4 v[184:187], v[108:109], off offset:320
	global_load_dwordx4 v[188:191], v[108:109], off offset:336
	v_add_f32_e32 v126, v118, v118
	v_add_f32_e32 v127, v119, v119
	v_add_f32_e32 v128, v120, v120
	v_add_f32_e32 v129, v121, v121
	v_add_f32_e32 v130, v122, v122
	v_add_f32_e32 v131, v123, v123
	v_add_f32_e32 v132, v124, v124
	v_add_f32_e32 v133, v125, v125
	v_mul_f32_e32 v126, 0x3fb8aa3b, v126
	v_mul_f32_e32 v127, 0x3fb8aa3b, v127
	v_mul_f32_e32 v128, 0x3fb8aa3b, v128
	v_mul_f32_e32 v129, 0x3fb8aa3b, v129
	v_mul_f32_e32 v130, 0x3fb8aa3b, v130
	v_mul_f32_e32 v131, 0x3fb8aa3b, v131
	v_mul_f32_e32 v132, 0x3fb8aa3b, v132
	v_mul_f32_e32 v133, 0x3fb8aa3b, v133
	v_exp_f32_e32 v126, v126
	v_exp_f32_e32 v127, v127
	v_exp_f32_e32 v128, v128
	v_exp_f32_e32 v129, v129
	v_exp_f32_e32 v130, v130
	v_exp_f32_e32 v131, v131
	v_exp_f32_e32 v132, v132
	v_exp_f32_e32 v133, v133
	v_add_f32_e32 v126, 1.0, v126
	v_add_f32_e32 v127, 1.0, v127
	v_add_f32_e32 v128, 1.0, v128
	v_add_f32_e32 v129, 1.0, v129
	v_add_f32_e32 v130, 1.0, v130
	v_add_f32_e32 v131, 1.0, v131
	v_add_f32_e32 v132, 1.0, v132
	v_add_f32_e32 v133, 1.0, v133
	v_rcp_f32_e32 v126, v126
	v_rcp_f32_e32 v127, v127
	v_rcp_f32_e32 v128, v128
	v_rcp_f32_e32 v129, v129
	v_rcp_f32_e32 v130, v130
	v_rcp_f32_e32 v131, v131
	v_rcp_f32_e32 v132, v132
	v_rcp_f32_e32 v133, v133
	v_fma_f32 v118, v126, -2.0, 1.0
	v_fma_f32 v119, v127, -2.0, 1.0
	v_fma_f32 v120, v128, -2.0, 1.0
	v_fma_f32 v121, v129, -2.0, 1.0
	v_fma_f32 v122, v130, -2.0, 1.0
	v_fma_f32 v123, v131, -2.0, 1.0
	v_fma_f32 v124, v132, -2.0, 1.0
	v_fma_f32 v125, v133, -2.0, 1.0
	s_nop 0
	v_cvt_pk_bf16_f32 v98, v118, v119
	v_cvt_pk_bf16_f32 v99, v120, v121
	v_cvt_pk_bf16_f32 v100, v122, v123
	v_cvt_pk_bf16_f32 v101, v124, v125
	v_cndmask_b32_e64 v98, 0, v98, s[2:3]
	v_cndmask_b32_e64 v99, 0, v99, s[2:3]
	v_cndmask_b32_e64 v100, 0, v100, s[2:3]
	v_cndmask_b32_e64 v101, 0, v101, s[2:3]
	s_nop 1
	v_mfma_f32_32x32x16_bf16 v[32:47], v[98:101], v[208:211], v[32:47]
	v_mfma_f32_32x32x16_bf16 v[48:63], v[98:101], v[222:225], v[48:63]
	global_load_dwordx4 v[208:211], v[112:113], off offset:-1984
	global_load_dwordx4 v[222:225], v[112:113], off offset:2112
	s_waitcnt vmcnt(14)
	v_lshlrev_b32_e32 v118, 16, v144
	v_and_b32_e32 v119, 0xffff0000, v144
	v_lshlrev_b32_e32 v120, 16, v145
	v_and_b32_e32 v121, 0xffff0000, v145
	v_lshlrev_b32_e32 v122, 16, v146
	v_and_b32_e32 v123, 0xffff0000, v146
	v_lshlrev_b32_e32 v124, 16, v147
	v_and_b32_e32 v125, 0xffff0000, v147
	v_cndmask_b32_e64 v148, 0, v148, s[4:5]
	v_cndmask_b32_e64 v149, 0, v149, s[4:5]
	v_cndmask_b32_e64 v150, 0, v150, s[4:5]
	v_cndmask_b32_e64 v151, 0, v151, s[4:5]
	v_lshlrev_b32_e32 v126, 16, v148
	v_and_b32_e32 v127, 0xffff0000, v148
	v_lshlrev_b32_e32 v128, 16, v149
	v_and_b32_e32 v129, 0xffff0000, v149
	v_lshlrev_b32_e32 v130, 16, v150
	v_and_b32_e32 v131, 0xffff0000, v150
	v_lshlrev_b32_e32 v132, 16, v151
	v_and_b32_e32 v133, 0xffff0000, v151
	global_load_dwordx4 v[144:147], v[102:103], off offset:3264
	global_load_dwordx4 v[148:151], v[104:105], off offset:192
	v_sub_f32_e32 v126, v126, v118
	v_sub_f32_e32 v127, v127, v119
	v_sub_f32_e32 v128, v128, v120
	v_sub_f32_e32 v129, v129, v121
	v_sub_f32_e32 v130, v130, v122
	v_sub_f32_e32 v131, v131, v123
	v_sub_f32_e32 v132, v132, v124
	v_sub_f32_e32 v133, v133, v125
	v_fmac_f32_e32 v118, v126, v152
	v_fmac_f32_e32 v119, v127, v153
	v_fmac_f32_e32 v120, v128, v154
	v_fmac_f32_e32 v121, v129, v155
	v_fmac_f32_e32 v122, v130, v156
	v_fmac_f32_e32 v123, v131, v157
	v_fmac_f32_e32 v124, v132, v158
	v_fmac_f32_e32 v125, v133, v159
	global_load_dwordx4 v[152:155], v[108:109], off offset:384
	global_load_dwordx4 v[156:159], v[108:109], off offset:400
	v_add_f32_e32 v126, v118, v118
	v_add_f32_e32 v127, v119, v119
	v_add_f32_e32 v128, v120, v120
	v_add_f32_e32 v129, v121, v121
	v_add_f32_e32 v130, v122, v122
	v_add_f32_e32 v131, v123, v123
	v_add_f32_e32 v132, v124, v124
	v_add_f32_e32 v133, v125, v125
	v_mul_f32_e32 v126, 0x3fb8aa3b, v126
	v_mul_f32_e32 v127, 0x3fb8aa3b, v127
	v_mul_f32_e32 v128, 0x3fb8aa3b, v128
	v_mul_f32_e32 v129, 0x3fb8aa3b, v129
	v_mul_f32_e32 v130, 0x3fb8aa3b, v130
	v_mul_f32_e32 v131, 0x3fb8aa3b, v131
	v_mul_f32_e32 v132, 0x3fb8aa3b, v132
	v_mul_f32_e32 v133, 0x3fb8aa3b, v133
	v_exp_f32_e32 v126, v126
	v_exp_f32_e32 v127, v127
	v_exp_f32_e32 v128, v128
	v_exp_f32_e32 v129, v129
	v_exp_f32_e32 v130, v130
	v_exp_f32_e32 v131, v131
	v_exp_f32_e32 v132, v132
	v_exp_f32_e32 v133, v133
	v_add_f32_e32 v126, 1.0, v126
	v_add_f32_e32 v127, 1.0, v127
	v_add_f32_e32 v128, 1.0, v128
	v_add_f32_e32 v129, 1.0, v129
	v_add_f32_e32 v130, 1.0, v130
	v_add_f32_e32 v131, 1.0, v131
	v_add_f32_e32 v132, 1.0, v132
	v_add_f32_e32 v133, 1.0, v133
	v_rcp_f32_e32 v126, v126
	v_rcp_f32_e32 v127, v127
	v_rcp_f32_e32 v128, v128
	v_rcp_f32_e32 v129, v129
	v_rcp_f32_e32 v130, v130
	v_rcp_f32_e32 v131, v131
	v_rcp_f32_e32 v132, v132
	v_rcp_f32_e32 v133, v133
	v_fma_f32 v118, v126, -2.0, 1.0
	v_fma_f32 v119, v127, -2.0, 1.0
	v_fma_f32 v120, v128, -2.0, 1.0
	v_fma_f32 v121, v129, -2.0, 1.0
	v_fma_f32 v122, v130, -2.0, 1.0
	v_fma_f32 v123, v131, -2.0, 1.0
	v_fma_f32 v124, v132, -2.0, 1.0
	v_fma_f32 v125, v133, -2.0, 1.0
	s_nop 0
	v_cvt_pk_bf16_f32 v98, v118, v119
	v_cvt_pk_bf16_f32 v99, v120, v121
	v_cvt_pk_bf16_f32 v100, v122, v123
	v_cvt_pk_bf16_f32 v101, v124, v125
	v_cndmask_b32_e64 v98, 0, v98, s[2:3]
	v_cndmask_b32_e64 v99, 0, v99, s[2:3]
	v_cndmask_b32_e64 v100, 0, v100, s[2:3]
	v_cndmask_b32_e64 v101, 0, v101, s[2:3]
	s_nop 1
	v_mfma_f32_32x32x16_bf16 v[32:47], v[98:101], v[226:229], v[32:47]
	v_mfma_f32_32x32x16_bf16 v[48:63], v[98:101], v[238:241], v[48:63]
	global_load_dwordx4 v[226:229], v[112:113], off offset:-1952
	global_load_dwordx4 v[238:241], v[112:113], off offset:2144
	s_waitcnt vmcnt(14)
	v_lshlrev_b32_e32 v118, 16, v160
	v_and_b32_e32 v119, 0xffff0000, v160
	v_lshlrev_b32_e32 v120, 16, v161
	v_and_b32_e32 v121, 0xffff0000, v161
	v_lshlrev_b32_e32 v122, 16, v162
	v_and_b32_e32 v123, 0xffff0000, v162
	v_lshlrev_b32_e32 v124, 16, v163
	v_and_b32_e32 v125, 0xffff0000, v163
	v_cndmask_b32_e64 v164, 0, v164, s[4:5]
	v_cndmask_b32_e64 v165, 0, v165, s[4:5]
	v_cndmask_b32_e64 v166, 0, v166, s[4:5]
	v_cndmask_b32_e64 v167, 0, v167, s[4:5]
	v_lshlrev_b32_e32 v126, 16, v164
	v_and_b32_e32 v127, 0xffff0000, v164
	v_lshlrev_b32_e32 v128, 16, v165
	v_and_b32_e32 v129, 0xffff0000, v165
	v_lshlrev_b32_e32 v130, 16, v166
	v_and_b32_e32 v131, 0xffff0000, v166
	v_lshlrev_b32_e32 v132, 16, v167
	v_and_b32_e32 v133, 0xffff0000, v167
	global_load_dwordx4 v[160:163], v[102:103], off offset:3296
	global_load_dwordx4 v[164:167], v[104:105], off offset:224
	v_sub_f32_e32 v126, v126, v118
	v_sub_f32_e32 v127, v127, v119
	v_sub_f32_e32 v128, v128, v120
	v_sub_f32_e32 v129, v129, v121
	v_sub_f32_e32 v130, v130, v122
	v_sub_f32_e32 v131, v131, v123
	v_sub_f32_e32 v132, v132, v124
	v_sub_f32_e32 v133, v133, v125
	v_fmac_f32_e32 v118, v126, v168
	v_fmac_f32_e32 v119, v127, v169
	v_fmac_f32_e32 v120, v128, v170
	v_fmac_f32_e32 v121, v129, v171
	v_fmac_f32_e32 v122, v130, v172
	v_fmac_f32_e32 v123, v131, v173
	v_fmac_f32_e32 v124, v132, v174
	v_fmac_f32_e32 v125, v133, v175
	global_load_dwordx4 v[168:171], v[108:109], off offset:448
	global_load_dwordx4 v[172:175], v[108:109], off offset:464
	v_cvt_pk_bf16_f32 v98, v118, v119
	v_cvt_pk_bf16_f32 v99, v120, v121
	v_cvt_pk_bf16_f32 v100, v122, v123
	v_cvt_pk_bf16_f32 v101, v124, v125
	v_cndmask_b32_e64 v98, 0, v98, s[2:3]
	v_cndmask_b32_e64 v99, 0, v99, s[2:3]
	v_cndmask_b32_e64 v100, 0, v100, s[2:3]
	v_cndmask_b32_e64 v101, 0, v101, s[2:3]
	s_nop 1
	v_mfma_f32_32x32x16_bf16 v[0:15], v[98:101], v[192:195], 0
	v_mfma_f32_32x32x16_bf16 v[16:31], v[98:101], v[196:199], 0
	global_load_dwordx4 v[192:195], v[114:115], off
	global_load_dwordx4 v[196:199], v[116:117], off
	s_waitcnt vmcnt(14)
	v_lshlrev_b32_e32 v118, 16, v176
	v_and_b32_e32 v119, 0xffff0000, v176
	v_lshlrev_b32_e32 v120, 16, v177
	v_and_b32_e32 v121, 0xffff0000, v177
	v_lshlrev_b32_e32 v122, 16, v178
	v_and_b32_e32 v123, 0xffff0000, v178
	v_lshlrev_b32_e32 v124, 16, v179
	v_and_b32_e32 v125, 0xffff0000, v179
	v_cndmask_b32_e64 v180, 0, v180, s[4:5]
	v_cndmask_b32_e64 v181, 0, v181, s[4:5]
	v_cndmask_b32_e64 v182, 0, v182, s[4:5]
	v_cndmask_b32_e64 v183, 0, v183, s[4:5]
	v_lshlrev_b32_e32 v126, 16, v180
	v_and_b32_e32 v127, 0xffff0000, v180
	v_lshlrev_b32_e32 v128, 16, v181
	v_and_b32_e32 v129, 0xffff0000, v181
	v_lshlrev_b32_e32 v130, 16, v182
	v_and_b32_e32 v131, 0xffff0000, v182
	v_lshlrev_b32_e32 v132, 16, v183
	v_and_b32_e32 v133, 0xffff0000, v183
	global_load_dwordx4 v[176:179], v[102:103], off offset:3328
	global_load_dwordx4 v[180:183], v[104:105], off offset:256
	v_sub_f32_e32 v126, v126, v118
	v_sub_f32_e32 v127, v127, v119
	v_sub_f32_e32 v128, v128, v120
	v_sub_f32_e32 v129, v129, v121
	v_sub_f32_e32 v130, v130, v122
	v_sub_f32_e32 v131, v131, v123
	v_sub_f32_e32 v132, v132, v124
	v_sub_f32_e32 v133, v133, v125
	v_fmac_f32_e32 v118, v126, v184
	v_fmac_f32_e32 v119, v127, v185
	v_fmac_f32_e32 v120, v128, v186
	v_fmac_f32_e32 v121, v129, v187
	v_fmac_f32_e32 v122, v130, v188
	v_fmac_f32_e32 v123, v131, v189
	v_fmac_f32_e32 v124, v132, v190
	v_fmac_f32_e32 v125, v133, v191
	global_load_dwordx4 v[184:187], v[108:109], off offset:512
	global_load_dwordx4 v[188:191], v[108:109], off offset:528
	v_cvt_pk_bf16_f32 v98, v118, v119
	v_cvt_pk_bf16_f32 v99, v120, v121
	v_cvt_pk_bf16_f32 v100, v122, v123
	v_cvt_pk_bf16_f32 v101, v124, v125
	v_cndmask_b32_e64 v98, 0, v98, s[2:3]
	v_cndmask_b32_e64 v99, 0, v99, s[2:3]
	v_cndmask_b32_e64 v100, 0, v100, s[2:3]
	v_cndmask_b32_e64 v101, 0, v101, s[2:3]
	s_nop 1
	v_mfma_f32_32x32x16_bf16 v[0:15], v[98:101], v[200:203], v[0:15]
	v_mfma_f32_32x32x16_bf16 v[16:31], v[98:101], v[204:207], v[16:31]
	global_load_dwordx4 v[200:203], v[114:115], off offset:32
	global_load_dwordx4 v[204:207], v[116:117], off offset:32
	s_waitcnt vmcnt(14)
	v_lshlrev_b32_e32 v118, 16, v144
	v_and_b32_e32 v119, 0xffff0000, v144
	v_lshlrev_b32_e32 v120, 16, v145
	v_and_b32_e32 v121, 0xffff0000, v145
	v_lshlrev_b32_e32 v122, 16, v146
	v_and_b32_e32 v123, 0xffff0000, v146
	v_lshlrev_b32_e32 v124, 16, v147
	v_and_b32_e32 v125, 0xffff0000, v147
	v_cndmask_b32_e64 v148, 0, v148, s[4:5]
	v_cndmask_b32_e64 v149, 0, v149, s[4:5]
	v_cndmask_b32_e64 v150, 0, v150, s[4:5]
	v_cndmask_b32_e64 v151, 0, v151, s[4:5]
	v_lshlrev_b32_e32 v126, 16, v148
	v_and_b32_e32 v127, 0xffff0000, v148
	v_lshlrev_b32_e32 v128, 16, v149
	v_and_b32_e32 v129, 0xffff0000, v149
	v_lshlrev_b32_e32 v130, 16, v150
	v_and_b32_e32 v131, 0xffff0000, v150
	v_lshlrev_b32_e32 v132, 16, v151
	v_and_b32_e32 v133, 0xffff0000, v151
	global_load_dwordx4 v[144:147], v[102:103], off offset:3360
	global_load_dwordx4 v[148:151], v[104:105], off offset:288
	v_sub_f32_e32 v126, v126, v118
	v_sub_f32_e32 v127, v127, v119
	v_sub_f32_e32 v128, v128, v120
	v_sub_f32_e32 v129, v129, v121
	v_sub_f32_e32 v130, v130, v122
	v_sub_f32_e32 v131, v131, v123
	v_sub_f32_e32 v132, v132, v124
	v_sub_f32_e32 v133, v133, v125
	v_fmac_f32_e32 v118, v126, v152
	v_fmac_f32_e32 v119, v127, v153
	v_fmac_f32_e32 v120, v128, v154
	v_fmac_f32_e32 v121, v129, v155
	v_fmac_f32_e32 v122, v130, v156
	v_fmac_f32_e32 v123, v131, v157
	v_fmac_f32_e32 v124, v132, v158
	v_fmac_f32_e32 v125, v133, v159
	global_load_dwordx4 v[152:155], v[108:109], off offset:576
	global_load_dwordx4 v[156:159], v[108:109], off offset:592
	v_cvt_pk_bf16_f32 v98, v118, v119
	v_cvt_pk_bf16_f32 v99, v120, v121
	v_cvt_pk_bf16_f32 v100, v122, v123
	v_cvt_pk_bf16_f32 v101, v124, v125
	v_cndmask_b32_e64 v98, 0, v98, s[2:3]
	v_cndmask_b32_e64 v99, 0, v99, s[2:3]
	v_cndmask_b32_e64 v100, 0, v100, s[2:3]
	v_cndmask_b32_e64 v101, 0, v101, s[2:3]
	s_nop 1
	v_mfma_f32_32x32x16_bf16 v[0:15], v[98:101], v[208:211], v[0:15]
	v_mfma_f32_32x32x16_bf16 v[16:31], v[98:101], v[222:225], v[16:31]
	global_load_dwordx4 v[208:211], v[114:115], off offset:64
	global_load_dwordx4 v[222:225], v[116:117], off offset:64
	s_waitcnt vmcnt(14)
	v_lshlrev_b32_e32 v118, 16, v160
	v_and_b32_e32 v119, 0xffff0000, v160
	v_lshlrev_b32_e32 v120, 16, v161
	v_and_b32_e32 v121, 0xffff0000, v161
	v_lshlrev_b32_e32 v122, 16, v162
	v_and_b32_e32 v123, 0xffff0000, v162
	v_lshlrev_b32_e32 v124, 16, v163
	v_and_b32_e32 v125, 0xffff0000, v163
	v_cndmask_b32_e64 v164, 0, v164, s[4:5]
	v_cndmask_b32_e64 v165, 0, v165, s[4:5]
	v_cndmask_b32_e64 v166, 0, v166, s[4:5]
	v_cndmask_b32_e64 v167, 0, v167, s[4:5]
	v_lshlrev_b32_e32 v126, 16, v164
	v_and_b32_e32 v127, 0xffff0000, v164
	v_lshlrev_b32_e32 v128, 16, v165
	v_and_b32_e32 v129, 0xffff0000, v165
	v_lshlrev_b32_e32 v130, 16, v166
	v_and_b32_e32 v131, 0xffff0000, v166
	v_lshlrev_b32_e32 v132, 16, v167
	v_and_b32_e32 v133, 0xffff0000, v167
	global_load_dwordx4 v[160:163], v[102:103], off offset:3392
	global_load_dwordx4 v[164:167], v[104:105], off offset:320
	v_sub_f32_e32 v126, v126, v118
	v_sub_f32_e32 v127, v127, v119
	v_sub_f32_e32 v128, v128, v120
	v_sub_f32_e32 v129, v129, v121
	v_sub_f32_e32 v130, v130, v122
	v_sub_f32_e32 v131, v131, v123
	v_sub_f32_e32 v132, v132, v124
	v_sub_f32_e32 v133, v133, v125
	v_fmac_f32_e32 v118, v126, v168
	v_fmac_f32_e32 v119, v127, v169
	v_fmac_f32_e32 v120, v128, v170
	v_fmac_f32_e32 v121, v129, v171
	v_fmac_f32_e32 v122, v130, v172
	v_fmac_f32_e32 v123, v131, v173
	v_fmac_f32_e32 v124, v132, v174
	v_fmac_f32_e32 v125, v133, v175
	global_load_dwordx4 v[168:171], v[108:109], off offset:640
	global_load_dwordx4 v[172:175], v[108:109], off offset:656
	v_cvt_pk_bf16_f32 v98, v118, v119
	v_cvt_pk_bf16_f32 v99, v120, v121
	v_cvt_pk_bf16_f32 v100, v122, v123
	v_cvt_pk_bf16_f32 v101, v124, v125
	v_cndmask_b32_e64 v98, 0, v98, s[2:3]
	v_cndmask_b32_e64 v99, 0, v99, s[2:3]
	v_cndmask_b32_e64 v100, 0, v100, s[2:3]
	v_cndmask_b32_e64 v101, 0, v101, s[2:3]
	s_nop 1
	v_mfma_f32_32x32x16_bf16 v[0:15], v[98:101], v[226:229], v[0:15]
	v_mfma_f32_32x32x16_bf16 v[16:31], v[98:101], v[238:241], v[16:31]
	global_load_dwordx4 v[226:229], v[114:115], off offset:96
	global_load_dwordx4 v[238:241], v[116:117], off offset:96
	s_waitcnt vmcnt(14)
	v_lshlrev_b32_e32 v118, 16, v176
	v_and_b32_e32 v119, 0xffff0000, v176
	v_lshlrev_b32_e32 v120, 16, v177
	v_and_b32_e32 v121, 0xffff0000, v177
	v_lshlrev_b32_e32 v122, 16, v178
	v_and_b32_e32 v123, 0xffff0000, v178
	v_lshlrev_b32_e32 v124, 16, v179
	v_and_b32_e32 v125, 0xffff0000, v179
	v_cndmask_b32_e64 v180, 0, v180, s[4:5]
	v_cndmask_b32_e64 v181, 0, v181, s[4:5]
	v_cndmask_b32_e64 v182, 0, v182, s[4:5]
	v_cndmask_b32_e64 v183, 0, v183, s[4:5]
	v_lshlrev_b32_e32 v126, 16, v180
	v_and_b32_e32 v127, 0xffff0000, v180
	v_lshlrev_b32_e32 v128, 16, v181
	v_and_b32_e32 v129, 0xffff0000, v181
	v_lshlrev_b32_e32 v130, 16, v182
	v_and_b32_e32 v131, 0xffff0000, v182
	v_lshlrev_b32_e32 v132, 16, v183
	v_and_b32_e32 v133, 0xffff0000, v183
	global_load_dwordx4 v[176:179], v[102:103], off offset:3424
	global_load_dwordx4 v[180:183], v[104:105], off offset:352
	v_sub_f32_e32 v126, v126, v118
	v_sub_f32_e32 v127, v127, v119
	v_sub_f32_e32 v128, v128, v120
	v_sub_f32_e32 v129, v129, v121
	v_sub_f32_e32 v130, v130, v122
	v_sub_f32_e32 v131, v131, v123
	v_sub_f32_e32 v132, v132, v124
	v_sub_f32_e32 v133, v133, v125
	v_fmac_f32_e32 v118, v126, v184
	v_fmac_f32_e32 v119, v127, v185
	v_fmac_f32_e32 v120, v128, v186
	v_fmac_f32_e32 v121, v129, v187
	v_fmac_f32_e32 v122, v130, v188
	v_fmac_f32_e32 v123, v131, v189
	v_fmac_f32_e32 v124, v132, v190
	v_fmac_f32_e32 v125, v133, v191
	global_load_dwordx4 v[184:187], v[108:109], off offset:704
	global_load_dwordx4 v[188:191], v[108:109], off offset:720
	v_mul_f32_e32 v126, 0xbfb8aa3b, v118
	v_mul_f32_e32 v127, 0xbfb8aa3b, v119
	v_mul_f32_e32 v128, 0xbfb8aa3b, v120
	v_mul_f32_e32 v129, 0xbfb8aa3b, v121
	v_mul_f32_e32 v130, 0xbfb8aa3b, v122
	v_mul_f32_e32 v131, 0xbfb8aa3b, v123
	v_mul_f32_e32 v132, 0xbfb8aa3b, v124
	v_mul_f32_e32 v133, 0xbfb8aa3b, v125
	v_exp_f32_e32 v126, v126
	v_exp_f32_e32 v127, v127
	v_exp_f32_e32 v128, v128
	v_exp_f32_e32 v129, v129
	v_exp_f32_e32 v130, v130
	v_exp_f32_e32 v131, v131
	v_exp_f32_e32 v132, v132
	v_exp_f32_e32 v133, v133
	v_add_f32_e32 v126, 1.0, v126
	v_add_f32_e32 v127, 1.0, v127
	v_add_f32_e32 v128, 1.0, v128
	v_add_f32_e32 v129, 1.0, v129
	v_add_f32_e32 v130, 1.0, v130
	v_add_f32_e32 v131, 1.0, v131
	v_add_f32_e32 v132, 1.0, v132
	v_add_f32_e32 v133, 1.0, v133
	v_rcp_f32_e32 v126, v126
	v_rcp_f32_e32 v127, v127
	v_rcp_f32_e32 v128, v128
	v_rcp_f32_e32 v129, v129
	v_rcp_f32_e32 v130, v130
	v_rcp_f32_e32 v131, v131
	v_rcp_f32_e32 v132, v132
	v_rcp_f32_e32 v133, v133
	s_nop 0
	v_cvt_pk_bf16_f32 v98, v126, v127
	v_cvt_pk_bf16_f32 v99, v128, v129
	v_cvt_pk_bf16_f32 v100, v130, v131
	v_cvt_pk_bf16_f32 v101, v132, v133
	v_cndmask_b32_e64 v98, 0, v98, s[2:3]
	v_cndmask_b32_e64 v99, 0, v99, s[2:3]
	v_cndmask_b32_e64 v100, 0, v100, s[2:3]
	v_cndmask_b32_e64 v101, 0, v101, s[2:3]
	s_nop 1
	v_mfma_f32_32x32x16_bf16 v[80:95], v[98:101], v[192:195], 0
	v_mfma_f32_32x32x16_bf16 v[64:79], v[98:101], v[196:199], 0
	global_load_dwordx4 v[192:195], v[114:115], off offset:128
	global_load_dwordx4 v[196:199], v[116:117], off offset:128
	s_waitcnt vmcnt(14)
	v_lshlrev_b32_e32 v118, 16, v144
	v_and_b32_e32 v119, 0xffff0000, v144
	v_lshlrev_b32_e32 v120, 16, v145
	v_and_b32_e32 v121, 0xffff0000, v145
	v_lshlrev_b32_e32 v122, 16, v146
	v_and_b32_e32 v123, 0xffff0000, v146
	v_lshlrev_b32_e32 v124, 16, v147
	v_and_b32_e32 v125, 0xffff0000, v147
	v_cndmask_b32_e64 v148, 0, v148, s[4:5]
	v_cndmask_b32_e64 v149, 0, v149, s[4:5]
	v_cndmask_b32_e64 v150, 0, v150, s[4:5]
	v_cndmask_b32_e64 v151, 0, v151, s[4:5]
	v_lshlrev_b32_e32 v126, 16, v148
	v_and_b32_e32 v127, 0xffff0000, v148
	v_lshlrev_b32_e32 v128, 16, v149
	v_and_b32_e32 v129, 0xffff0000, v149
	v_lshlrev_b32_e32 v130, 16, v150
	v_and_b32_e32 v131, 0xffff0000, v150
	v_lshlrev_b32_e32 v132, 16, v151
	v_and_b32_e32 v133, 0xffff0000, v151
	global_load_dwordx4 v[144:147], v[102:103], off offset:3456
	global_load_dwordx4 v[148:151], v[104:105], off offset:384
	v_sub_f32_e32 v126, v126, v118
	v_sub_f32_e32 v127, v127, v119
	v_sub_f32_e32 v128, v128, v120
	v_sub_f32_e32 v129, v129, v121
	v_sub_f32_e32 v130, v130, v122
	v_sub_f32_e32 v131, v131, v123
	v_sub_f32_e32 v132, v132, v124
	v_sub_f32_e32 v133, v133, v125
	v_fmac_f32_e32 v118, v126, v152
	v_fmac_f32_e32 v119, v127, v153
	v_fmac_f32_e32 v120, v128, v154
	v_fmac_f32_e32 v121, v129, v155
	v_fmac_f32_e32 v122, v130, v156
	v_fmac_f32_e32 v123, v131, v157
	v_fmac_f32_e32 v124, v132, v158
	v_fmac_f32_e32 v125, v133, v159
	global_load_dwordx4 v[152:155], v[108:109], off offset:768
	global_load_dwordx4 v[156:159], v[108:109], off offset:784
	v_mul_f32_e32 v126, 0xbfb8aa3b, v118
	v_mul_f32_e32 v127, 0xbfb8aa3b, v119
	v_mul_f32_e32 v128, 0xbfb8aa3b, v120
	v_mul_f32_e32 v129, 0xbfb8aa3b, v121
	v_mul_f32_e32 v130, 0xbfb8aa3b, v122
	v_mul_f32_e32 v131, 0xbfb8aa3b, v123
	v_mul_f32_e32 v132, 0xbfb8aa3b, v124
	v_mul_f32_e32 v133, 0xbfb8aa3b, v125
	v_exp_f32_e32 v126, v126
	v_exp_f32_e32 v127, v127
	v_exp_f32_e32 v128, v128
	v_exp_f32_e32 v129, v129
	v_exp_f32_e32 v130, v130
	v_exp_f32_e32 v131, v131
	v_exp_f32_e32 v132, v132
	v_exp_f32_e32 v133, v133
	v_add_f32_e32 v126, 1.0, v126
	v_add_f32_e32 v127, 1.0, v127
	v_add_f32_e32 v128, 1.0, v128
	v_add_f32_e32 v129, 1.0, v129
	v_add_f32_e32 v130, 1.0, v130
	v_add_f32_e32 v131, 1.0, v131
	v_add_f32_e32 v132, 1.0, v132
	v_add_f32_e32 v133, 1.0, v133
	v_rcp_f32_e32 v126, v126
	v_rcp_f32_e32 v127, v127
	v_rcp_f32_e32 v128, v128
	v_rcp_f32_e32 v129, v129
	v_rcp_f32_e32 v130, v130
	v_rcp_f32_e32 v131, v131
	v_rcp_f32_e32 v132, v132
	v_rcp_f32_e32 v133, v133
	s_nop 0
	v_cvt_pk_bf16_f32 v98, v126, v127
	v_cvt_pk_bf16_f32 v99, v128, v129
	v_cvt_pk_bf16_f32 v100, v130, v131
	v_cvt_pk_bf16_f32 v101, v132, v133
	v_cndmask_b32_e64 v98, 0, v98, s[2:3]
	v_cndmask_b32_e64 v99, 0, v99, s[2:3]
	v_cndmask_b32_e64 v100, 0, v100, s[2:3]
	v_cndmask_b32_e64 v101, 0, v101, s[2:3]
	s_nop 1
	v_mfma_f32_32x32x16_bf16 v[80:95], v[98:101], v[200:203], v[80:95]
	v_mfma_f32_32x32x16_bf16 v[64:79], v[98:101], v[204:207], v[64:79]
	global_load_dwordx4 v[200:203], v[114:115], off offset:160
	global_load_dwordx4 v[204:207], v[116:117], off offset:160
	s_waitcnt vmcnt(14)
	v_lshlrev_b32_e32 v118, 16, v160
	v_and_b32_e32 v119, 0xffff0000, v160
	v_lshlrev_b32_e32 v120, 16, v161
	v_and_b32_e32 v121, 0xffff0000, v161
	v_lshlrev_b32_e32 v122, 16, v162
	v_and_b32_e32 v123, 0xffff0000, v162
	v_lshlrev_b32_e32 v124, 16, v163
	v_and_b32_e32 v125, 0xffff0000, v163
	v_cndmask_b32_e64 v164, 0, v164, s[4:5]
	v_cndmask_b32_e64 v165, 0, v165, s[4:5]
	v_cndmask_b32_e64 v166, 0, v166, s[4:5]
	v_cndmask_b32_e64 v167, 0, v167, s[4:5]
	v_lshlrev_b32_e32 v126, 16, v164
	v_and_b32_e32 v127, 0xffff0000, v164
	v_lshlrev_b32_e32 v128, 16, v165
	v_and_b32_e32 v129, 0xffff0000, v165
	v_lshlrev_b32_e32 v130, 16, v166
	v_and_b32_e32 v131, 0xffff0000, v166
	v_lshlrev_b32_e32 v132, 16, v167
	v_and_b32_e32 v133, 0xffff0000, v167
	global_load_dwordx4 v[160:163], v[102:103], off offset:3488
	global_load_dwordx4 v[164:167], v[104:105], off offset:416
	v_sub_f32_e32 v126, v126, v118
	v_sub_f32_e32 v127, v127, v119
	v_sub_f32_e32 v128, v128, v120
	v_sub_f32_e32 v129, v129, v121
	v_sub_f32_e32 v130, v130, v122
	v_sub_f32_e32 v131, v131, v123
	v_sub_f32_e32 v132, v132, v124
	v_sub_f32_e32 v133, v133, v125
	v_fmac_f32_e32 v118, v126, v168
	v_fmac_f32_e32 v119, v127, v169
	v_fmac_f32_e32 v120, v128, v170
	v_fmac_f32_e32 v121, v129, v171
	v_fmac_f32_e32 v122, v130, v172
	v_fmac_f32_e32 v123, v131, v173
	v_fmac_f32_e32 v124, v132, v174
	v_fmac_f32_e32 v125, v133, v175
	global_load_dwordx4 v[168:171], v[108:109], off offset:832
	global_load_dwordx4 v[172:175], v[108:109], off offset:848
	v_mul_f32_e32 v126, 0xbfb8aa3b, v118
	v_mul_f32_e32 v127, 0xbfb8aa3b, v119
	v_mul_f32_e32 v128, 0xbfb8aa3b, v120
	v_mul_f32_e32 v129, 0xbfb8aa3b, v121
	v_mul_f32_e32 v130, 0xbfb8aa3b, v122
	v_mul_f32_e32 v131, 0xbfb8aa3b, v123
	v_mul_f32_e32 v132, 0xbfb8aa3b, v124
	v_mul_f32_e32 v133, 0xbfb8aa3b, v125
	v_exp_f32_e32 v126, v126
	v_exp_f32_e32 v127, v127
	v_exp_f32_e32 v128, v128
	v_exp_f32_e32 v129, v129
	v_exp_f32_e32 v130, v130
	v_exp_f32_e32 v131, v131
	v_exp_f32_e32 v132, v132
	v_exp_f32_e32 v133, v133
	v_add_f32_e32 v126, 1.0, v126
	v_add_f32_e32 v127, 1.0, v127
	v_add_f32_e32 v128, 1.0, v128
	v_add_f32_e32 v129, 1.0, v129
	v_add_f32_e32 v130, 1.0, v130
	v_add_f32_e32 v131, 1.0, v131
	v_add_f32_e32 v132, 1.0, v132
	v_add_f32_e32 v133, 1.0, v133
	v_rcp_f32_e32 v126, v126
	v_rcp_f32_e32 v127, v127
	v_rcp_f32_e32 v128, v128
	v_rcp_f32_e32 v129, v129
	v_rcp_f32_e32 v130, v130
	v_rcp_f32_e32 v131, v131
	v_rcp_f32_e32 v132, v132
	v_rcp_f32_e32 v133, v133
	s_nop 0
	v_cvt_pk_bf16_f32 v98, v126, v127
	v_cvt_pk_bf16_f32 v99, v128, v129
	v_cvt_pk_bf16_f32 v100, v130, v131
	v_cvt_pk_bf16_f32 v101, v132, v133
	v_cndmask_b32_e64 v98, 0, v98, s[2:3]
	v_cndmask_b32_e64 v99, 0, v99, s[2:3]
	v_cndmask_b32_e64 v100, 0, v100, s[2:3]
	v_cndmask_b32_e64 v101, 0, v101, s[2:3]
	s_nop 1
	v_mfma_f32_32x32x16_bf16 v[80:95], v[98:101], v[208:211], v[80:95]
	v_mfma_f32_32x32x16_bf16 v[64:79], v[98:101], v[222:225], v[64:79]
	global_load_dwordx4 v[208:211], v[114:115], off offset:192
	global_load_dwordx4 v[222:225], v[116:117], off offset:192
	s_waitcnt vmcnt(14)
	v_lshlrev_b32_e32 v118, 16, v176
	v_and_b32_e32 v119, 0xffff0000, v176
	v_lshlrev_b32_e32 v120, 16, v177
	v_and_b32_e32 v121, 0xffff0000, v177
	v_lshlrev_b32_e32 v122, 16, v178
	v_and_b32_e32 v123, 0xffff0000, v178
	v_lshlrev_b32_e32 v124, 16, v179
	v_and_b32_e32 v125, 0xffff0000, v179
	v_cndmask_b32_e64 v180, 0, v180, s[4:5]
	v_cndmask_b32_e64 v181, 0, v181, s[4:5]
	v_cndmask_b32_e64 v182, 0, v182, s[4:5]
	v_cndmask_b32_e64 v183, 0, v183, s[4:5]
	v_lshlrev_b32_e32 v126, 16, v180
	v_and_b32_e32 v127, 0xffff0000, v180
	v_lshlrev_b32_e32 v128, 16, v181
	v_and_b32_e32 v129, 0xffff0000, v181
	v_lshlrev_b32_e32 v130, 16, v182
	v_and_b32_e32 v131, 0xffff0000, v182
	v_lshlrev_b32_e32 v132, 16, v183
	v_and_b32_e32 v133, 0xffff0000, v183
	global_load_dwordx4 v[176:179], v[102:103], off offset:3520
	global_load_dwordx4 v[180:183], v[104:105], off offset:448
	v_sub_f32_e32 v126, v126, v118
	v_sub_f32_e32 v127, v127, v119
	v_sub_f32_e32 v128, v128, v120
	v_sub_f32_e32 v129, v129, v121
	v_sub_f32_e32 v130, v130, v122
	v_sub_f32_e32 v131, v131, v123
	v_sub_f32_e32 v132, v132, v124
	v_sub_f32_e32 v133, v133, v125
	v_fmac_f32_e32 v118, v126, v184
	v_fmac_f32_e32 v119, v127, v185
	v_fmac_f32_e32 v120, v128, v186
	v_fmac_f32_e32 v121, v129, v187
	v_fmac_f32_e32 v122, v130, v188
	v_fmac_f32_e32 v123, v131, v189
	v_fmac_f32_e32 v124, v132, v190
	v_fmac_f32_e32 v125, v133, v191
	global_load_dwordx4 v[184:187], v[108:109], off offset:896
	global_load_dwordx4 v[188:191], v[108:109], off offset:912
	v_mul_f32_e32 v126, 0xbfb8aa3b, v118
	v_mul_f32_e32 v127, 0xbfb8aa3b, v119
	v_mul_f32_e32 v128, 0xbfb8aa3b, v120
	v_mul_f32_e32 v129, 0xbfb8aa3b, v121
	v_mul_f32_e32 v130, 0xbfb8aa3b, v122
	v_mul_f32_e32 v131, 0xbfb8aa3b, v123
	v_mul_f32_e32 v132, 0xbfb8aa3b, v124
	v_mul_f32_e32 v133, 0xbfb8aa3b, v125
	v_exp_f32_e32 v126, v126
	v_exp_f32_e32 v127, v127
	v_exp_f32_e32 v128, v128
	v_exp_f32_e32 v129, v129
	v_exp_f32_e32 v130, v130
	v_exp_f32_e32 v131, v131
	v_exp_f32_e32 v132, v132
	v_exp_f32_e32 v133, v133
	v_add_f32_e32 v126, 1.0, v126
	v_add_f32_e32 v127, 1.0, v127
	v_add_f32_e32 v128, 1.0, v128
	v_add_f32_e32 v129, 1.0, v129
	v_add_f32_e32 v130, 1.0, v130
	v_add_f32_e32 v131, 1.0, v131
	v_add_f32_e32 v132, 1.0, v132
	v_add_f32_e32 v133, 1.0, v133
	v_rcp_f32_e32 v126, v126
	v_rcp_f32_e32 v127, v127
	v_rcp_f32_e32 v128, v128
	v_rcp_f32_e32 v129, v129
	v_rcp_f32_e32 v130, v130
	v_rcp_f32_e32 v131, v131
	v_rcp_f32_e32 v132, v132
	v_rcp_f32_e32 v133, v133
	s_nop 0
	v_cvt_pk_bf16_f32 v98, v126, v127
	v_cvt_pk_bf16_f32 v99, v128, v129
	v_cvt_pk_bf16_f32 v100, v130, v131
	v_cvt_pk_bf16_f32 v101, v132, v133
	v_cndmask_b32_e64 v98, 0, v98, s[2:3]
	v_cndmask_b32_e64 v99, 0, v99, s[2:3]
	v_cndmask_b32_e64 v100, 0, v100, s[2:3]
	v_cndmask_b32_e64 v101, 0, v101, s[2:3]
	s_nop 1
	v_mfma_f32_32x32x16_bf16 v[80:95], v[98:101], v[226:229], v[80:95]
	v_mfma_f32_32x32x16_bf16 v[64:79], v[98:101], v[238:241], v[64:79]
	global_load_dwordx4 v[226:229], v[114:115], off offset:224
	global_load_dwordx4 v[238:241], v[116:117], off offset:224
	s_waitcnt vmcnt(14)
	v_lshlrev_b32_e32 v118, 16, v144
	v_and_b32_e32 v119, 0xffff0000, v144
	v_lshlrev_b32_e32 v120, 16, v145
	v_and_b32_e32 v121, 0xffff0000, v145
	v_lshlrev_b32_e32 v122, 16, v146
	v_and_b32_e32 v123, 0xffff0000, v146
	v_lshlrev_b32_e32 v124, 16, v147
	v_and_b32_e32 v125, 0xffff0000, v147
	v_cndmask_b32_e64 v148, 0, v148, s[4:5]
	v_cndmask_b32_e64 v149, 0, v149, s[4:5]
	v_cndmask_b32_e64 v150, 0, v150, s[4:5]
	v_cndmask_b32_e64 v151, 0, v151, s[4:5]
	v_lshlrev_b32_e32 v126, 16, v148
	v_and_b32_e32 v127, 0xffff0000, v148
	v_lshlrev_b32_e32 v128, 16, v149
	v_and_b32_e32 v129, 0xffff0000, v149
	v_lshlrev_b32_e32 v130, 16, v150
	v_and_b32_e32 v131, 0xffff0000, v150
	v_lshlrev_b32_e32 v132, 16, v151
	v_and_b32_e32 v133, 0xffff0000, v151
	global_load_dwordx4 v[144:147], v[102:103], off offset:3552
	global_load_dwordx4 v[148:151], v[104:105], off offset:480
	v_sub_f32_e32 v126, v126, v118
	v_sub_f32_e32 v127, v127, v119
	v_sub_f32_e32 v128, v128, v120
	v_sub_f32_e32 v129, v129, v121
	v_sub_f32_e32 v130, v130, v122
	v_sub_f32_e32 v131, v131, v123
	v_sub_f32_e32 v132, v132, v124
	v_sub_f32_e32 v133, v133, v125
	v_fmac_f32_e32 v118, v126, v152
	v_fmac_f32_e32 v119, v127, v153
	v_fmac_f32_e32 v120, v128, v154
	v_fmac_f32_e32 v121, v129, v155
	v_fmac_f32_e32 v122, v130, v156
	v_fmac_f32_e32 v123, v131, v157
	v_fmac_f32_e32 v124, v132, v158
	v_fmac_f32_e32 v125, v133, v159
	global_load_dwordx4 v[152:155], v[108:109], off offset:960
	global_load_dwordx4 v[156:159], v[108:109], off offset:976
	v_mul_f32_e32 v126, 0xbfb8aa3b, v118
	v_mul_f32_e32 v127, 0xbfb8aa3b, v119
	v_mul_f32_e32 v128, 0xbfb8aa3b, v120
	v_mul_f32_e32 v129, 0xbfb8aa3b, v121
	v_mul_f32_e32 v130, 0xbfb8aa3b, v122
	v_mul_f32_e32 v131, 0xbfb8aa3b, v123
	v_mul_f32_e32 v132, 0xbfb8aa3b, v124
	v_mul_f32_e32 v133, 0xbfb8aa3b, v125
	v_exp_f32_e32 v126, v126
	v_exp_f32_e32 v127, v127
	v_exp_f32_e32 v128, v128
	v_exp_f32_e32 v129, v129
	v_exp_f32_e32 v130, v130
	v_exp_f32_e32 v131, v131
	v_exp_f32_e32 v132, v132
	v_exp_f32_e32 v133, v133
	v_add_f32_e32 v126, 1.0, v126
	v_add_f32_e32 v127, 1.0, v127
	v_add_f32_e32 v128, 1.0, v128
	v_add_f32_e32 v129, 1.0, v129
	v_add_f32_e32 v130, 1.0, v130
	v_add_f32_e32 v131, 1.0, v131
	v_add_f32_e32 v132, 1.0, v132
	v_add_f32_e32 v133, 1.0, v133
	v_rcp_f32_e32 v126, v126
	v_rcp_f32_e32 v127, v127
	v_rcp_f32_e32 v128, v128
	v_rcp_f32_e32 v129, v129
	v_rcp_f32_e32 v130, v130
	v_rcp_f32_e32 v131, v131
	v_rcp_f32_e32 v132, v132
	v_rcp_f32_e32 v133, v133
	s_nop 0
	v_cvt_pk_bf16_f32 v98, v126, v127
	v_cvt_pk_bf16_f32 v99, v128, v129
	v_cvt_pk_bf16_f32 v100, v130, v131
	v_cvt_pk_bf16_f32 v101, v132, v133
	v_cndmask_b32_e64 v98, 0, v98, s[2:3]
	v_cndmask_b32_e64 v99, 0, v99, s[2:3]
	v_cndmask_b32_e64 v100, 0, v100, s[2:3]
	v_cndmask_b32_e64 v101, 0, v101, s[2:3]
	s_nop 1
	v_mfma_f32_32x32x16_bf16 v[80:95], v[98:101], v[192:195], v[80:95]
	v_mfma_f32_32x32x16_bf16 v[64:79], v[98:101], v[196:199], v[64:79]
	s_waitcnt vmcnt(12)
	v_lshlrev_b32_e32 v118, 16, v160
	v_and_b32_e32 v119, 0xffff0000, v160
	v_lshlrev_b32_e32 v120, 16, v161
	v_and_b32_e32 v121, 0xffff0000, v161
	v_lshlrev_b32_e32 v122, 16, v162
	v_and_b32_e32 v123, 0xffff0000, v162
	v_lshlrev_b32_e32 v124, 16, v163
	v_and_b32_e32 v125, 0xffff0000, v163
	v_cndmask_b32_e64 v164, 0, v164, s[4:5]
	v_cndmask_b32_e64 v165, 0, v165, s[4:5]
	v_cndmask_b32_e64 v166, 0, v166, s[4:5]
	v_cndmask_b32_e64 v167, 0, v167, s[4:5]
	v_lshlrev_b32_e32 v126, 16, v164
	v_and_b32_e32 v127, 0xffff0000, v164
	v_lshlrev_b32_e32 v128, 16, v165
	v_and_b32_e32 v129, 0xffff0000, v165
	v_lshlrev_b32_e32 v130, 16, v166
	v_and_b32_e32 v131, 0xffff0000, v166
	v_lshlrev_b32_e32 v132, 16, v167
	v_and_b32_e32 v133, 0xffff0000, v167
	v_sub_f32_e32 v126, v126, v118
	v_sub_f32_e32 v127, v127, v119
	v_sub_f32_e32 v128, v128, v120
	v_sub_f32_e32 v129, v129, v121
	v_sub_f32_e32 v130, v130, v122
	v_sub_f32_e32 v131, v131, v123
	v_sub_f32_e32 v132, v132, v124
	v_sub_f32_e32 v133, v133, v125
	v_fmac_f32_e32 v118, v126, v168
	v_fmac_f32_e32 v119, v127, v169
	v_fmac_f32_e32 v120, v128, v170
	v_fmac_f32_e32 v121, v129, v171
	v_fmac_f32_e32 v122, v130, v172
	v_fmac_f32_e32 v123, v131, v173
	v_fmac_f32_e32 v124, v132, v174
	v_fmac_f32_e32 v125, v133, v175
	v_mul_f32_e32 v126, 0xbfb8aa3b, v118
	v_mul_f32_e32 v127, 0xbfb8aa3b, v119
	v_mul_f32_e32 v128, 0xbfb8aa3b, v120
	v_mul_f32_e32 v129, 0xbfb8aa3b, v121
	v_mul_f32_e32 v130, 0xbfb8aa3b, v122
	v_mul_f32_e32 v131, 0xbfb8aa3b, v123
	v_mul_f32_e32 v132, 0xbfb8aa3b, v124
	v_mul_f32_e32 v133, 0xbfb8aa3b, v125
	v_exp_f32_e32 v126, v126
	v_exp_f32_e32 v127, v127
	v_exp_f32_e32 v128, v128
	v_exp_f32_e32 v129, v129
	v_exp_f32_e32 v130, v130
	v_exp_f32_e32 v131, v131
	v_exp_f32_e32 v132, v132
	v_exp_f32_e32 v133, v133
	v_add_f32_e32 v126, 1.0, v126
	v_add_f32_e32 v127, 1.0, v127
	v_add_f32_e32 v128, 1.0, v128
	v_add_f32_e32 v129, 1.0, v129
	v_add_f32_e32 v130, 1.0, v130
	v_add_f32_e32 v131, 1.0, v131
	v_add_f32_e32 v132, 1.0, v132
	v_add_f32_e32 v133, 1.0, v133
	v_rcp_f32_e32 v126, v126
	v_rcp_f32_e32 v127, v127
	v_rcp_f32_e32 v128, v128
	v_rcp_f32_e32 v129, v129
	v_rcp_f32_e32 v130, v130
	v_rcp_f32_e32 v131, v131
	v_rcp_f32_e32 v132, v132
	v_rcp_f32_e32 v133, v133
	s_nop 0
	v_cvt_pk_bf16_f32 v98, v126, v127
	v_cvt_pk_bf16_f32 v99, v128, v129
	v_cvt_pk_bf16_f32 v100, v130, v131
	v_cvt_pk_bf16_f32 v101, v132, v133
	v_cndmask_b32_e64 v98, 0, v98, s[2:3]
	v_cndmask_b32_e64 v99, 0, v99, s[2:3]
	v_cndmask_b32_e64 v100, 0, v100, s[2:3]
	v_cndmask_b32_e64 v101, 0, v101, s[2:3]
	s_nop 1
	v_mfma_f32_32x32x16_bf16 v[80:95], v[98:101], v[200:203], v[80:95]
	v_mfma_f32_32x32x16_bf16 v[64:79], v[98:101], v[204:207], v[64:79]
	s_waitcnt vmcnt(6)
	v_lshlrev_b32_e32 v118, 16, v176
	v_and_b32_e32 v119, 0xffff0000, v176
	v_lshlrev_b32_e32 v120, 16, v177
	v_and_b32_e32 v121, 0xffff0000, v177
	v_lshlrev_b32_e32 v122, 16, v178
	v_and_b32_e32 v123, 0xffff0000, v178
	v_lshlrev_b32_e32 v124, 16, v179
	v_and_b32_e32 v125, 0xffff0000, v179
	v_cndmask_b32_e64 v180, 0, v180, s[4:5]
	v_cndmask_b32_e64 v181, 0, v181, s[4:5]
	v_cndmask_b32_e64 v182, 0, v182, s[4:5]
	v_cndmask_b32_e64 v183, 0, v183, s[4:5]
	v_lshlrev_b32_e32 v126, 16, v180
	v_and_b32_e32 v127, 0xffff0000, v180
	v_lshlrev_b32_e32 v128, 16, v181
	v_and_b32_e32 v129, 0xffff0000, v181
	v_lshlrev_b32_e32 v130, 16, v182
	v_and_b32_e32 v131, 0xffff0000, v182
	v_lshlrev_b32_e32 v132, 16, v183
	v_and_b32_e32 v133, 0xffff0000, v183
	v_sub_f32_e32 v126, v126, v118
	v_sub_f32_e32 v127, v127, v119
	v_sub_f32_e32 v128, v128, v120
	v_sub_f32_e32 v129, v129, v121
	v_sub_f32_e32 v130, v130, v122
	v_sub_f32_e32 v131, v131, v123
	v_sub_f32_e32 v132, v132, v124
	v_sub_f32_e32 v133, v133, v125
	v_fmac_f32_e32 v118, v126, v184
	v_fmac_f32_e32 v119, v127, v185
	v_fmac_f32_e32 v120, v128, v186
	v_fmac_f32_e32 v121, v129, v187
	v_fmac_f32_e32 v122, v130, v188
	v_fmac_f32_e32 v123, v131, v189
	v_fmac_f32_e32 v124, v132, v190
	v_fmac_f32_e32 v125, v133, v191
	v_mul_f32_e32 v126, 0xbfb8aa3b, v118
	v_mul_f32_e32 v127, 0xbfb8aa3b, v119
	v_mul_f32_e32 v128, 0xbfb8aa3b, v120
	v_mul_f32_e32 v129, 0xbfb8aa3b, v121
	v_mul_f32_e32 v130, 0xbfb8aa3b, v122
	v_mul_f32_e32 v131, 0xbfb8aa3b, v123
	v_mul_f32_e32 v132, 0xbfb8aa3b, v124
	v_mul_f32_e32 v133, 0xbfb8aa3b, v125
	v_exp_f32_e32 v126, v126
	v_exp_f32_e32 v127, v127
	v_exp_f32_e32 v128, v128
	v_exp_f32_e32 v129, v129
	v_exp_f32_e32 v130, v130
	v_exp_f32_e32 v131, v131
	v_exp_f32_e32 v132, v132
	v_exp_f32_e32 v133, v133
	v_add_f32_e32 v126, 1.0, v126
	v_add_f32_e32 v127, 1.0, v127
	v_add_f32_e32 v128, 1.0, v128
	v_add_f32_e32 v129, 1.0, v129
	v_add_f32_e32 v130, 1.0, v130
	v_add_f32_e32 v131, 1.0, v131
	v_add_f32_e32 v132, 1.0, v132
	v_add_f32_e32 v133, 1.0, v133
	v_rcp_f32_e32 v126, v126
	v_rcp_f32_e32 v127, v127
	v_rcp_f32_e32 v128, v128
	v_rcp_f32_e32 v129, v129
	v_rcp_f32_e32 v130, v130
	v_rcp_f32_e32 v131, v131
	v_rcp_f32_e32 v132, v132
	v_rcp_f32_e32 v133, v133
	s_nop 0
	v_cvt_pk_bf16_f32 v98, v126, v127
	v_cvt_pk_bf16_f32 v99, v128, v129
	v_cvt_pk_bf16_f32 v100, v130, v131
	v_cvt_pk_bf16_f32 v101, v132, v133
	v_cndmask_b32_e64 v98, 0, v98, s[2:3]
	v_cndmask_b32_e64 v99, 0, v99, s[2:3]
	v_cndmask_b32_e64 v100, 0, v100, s[2:3]
	v_cndmask_b32_e64 v101, 0, v101, s[2:3]
	s_nop 1
	v_mfma_f32_32x32x16_bf16 v[80:95], v[98:101], v[208:211], v[80:95]
	v_mfma_f32_32x32x16_bf16 v[64:79], v[98:101], v[222:225], v[64:79]
	s_waitcnt vmcnt(0)
	v_lshlrev_b32_e32 v118, 16, v144
	v_and_b32_e32 v119, 0xffff0000, v144
	v_lshlrev_b32_e32 v120, 16, v145
	v_and_b32_e32 v121, 0xffff0000, v145
	v_lshlrev_b32_e32 v122, 16, v146
	v_and_b32_e32 v123, 0xffff0000, v146
	v_lshlrev_b32_e32 v124, 16, v147
	v_and_b32_e32 v125, 0xffff0000, v147
	v_cndmask_b32_e64 v148, 0, v148, s[4:5]
	v_cndmask_b32_e64 v149, 0, v149, s[4:5]
	v_cndmask_b32_e64 v150, 0, v150, s[4:5]
	v_cndmask_b32_e64 v151, 0, v151, s[4:5]
	v_lshlrev_b32_e32 v126, 16, v148
	v_and_b32_e32 v127, 0xffff0000, v148
	v_lshlrev_b32_e32 v128, 16, v149
	v_and_b32_e32 v129, 0xffff0000, v149
	v_lshlrev_b32_e32 v130, 16, v150
	v_and_b32_e32 v131, 0xffff0000, v150
	v_lshlrev_b32_e32 v132, 16, v151
	v_and_b32_e32 v133, 0xffff0000, v151
	v_sub_f32_e32 v126, v126, v118
	v_sub_f32_e32 v127, v127, v119
	v_sub_f32_e32 v128, v128, v120
	v_sub_f32_e32 v129, v129, v121
	v_sub_f32_e32 v130, v130, v122
	v_sub_f32_e32 v131, v131, v123
	v_sub_f32_e32 v132, v132, v124
	v_sub_f32_e32 v133, v133, v125
	v_fmac_f32_e32 v118, v126, v152
	v_fmac_f32_e32 v119, v127, v153
	v_fmac_f32_e32 v120, v128, v154
	v_fmac_f32_e32 v121, v129, v155
	v_fmac_f32_e32 v122, v130, v156
	v_fmac_f32_e32 v123, v131, v157
	v_fmac_f32_e32 v124, v132, v158
	v_fmac_f32_e32 v125, v133, v159
	v_mul_f32_e32 v126, 0xbfb8aa3b, v118
	v_mul_f32_e32 v127, 0xbfb8aa3b, v119
	v_mul_f32_e32 v128, 0xbfb8aa3b, v120
	v_mul_f32_e32 v129, 0xbfb8aa3b, v121
	v_mul_f32_e32 v130, 0xbfb8aa3b, v122
	v_mul_f32_e32 v131, 0xbfb8aa3b, v123
	v_mul_f32_e32 v132, 0xbfb8aa3b, v124
	v_mul_f32_e32 v133, 0xbfb8aa3b, v125
	v_exp_f32_e32 v126, v126
	v_exp_f32_e32 v127, v127
	v_exp_f32_e32 v128, v128
	v_exp_f32_e32 v129, v129
	v_exp_f32_e32 v130, v130
	v_exp_f32_e32 v131, v131
	v_exp_f32_e32 v132, v132
	v_exp_f32_e32 v133, v133
	v_add_f32_e32 v126, 1.0, v126
	v_add_f32_e32 v127, 1.0, v127
	v_add_f32_e32 v128, 1.0, v128
	v_add_f32_e32 v129, 1.0, v129
	v_add_f32_e32 v130, 1.0, v130
	v_add_f32_e32 v131, 1.0, v131
	v_add_f32_e32 v132, 1.0, v132
	v_add_f32_e32 v133, 1.0, v133
	v_rcp_f32_e32 v126, v126
	v_rcp_f32_e32 v127, v127
	v_rcp_f32_e32 v128, v128
	v_rcp_f32_e32 v129, v129
	v_rcp_f32_e32 v130, v130
	v_rcp_f32_e32 v131, v131
	v_rcp_f32_e32 v132, v132
	v_rcp_f32_e32 v133, v133
	s_nop 0
	v_cvt_pk_bf16_f32 v98, v126, v127
	v_cvt_pk_bf16_f32 v99, v128, v129
	v_cvt_pk_bf16_f32 v100, v130, v131
	v_cvt_pk_bf16_f32 v101, v132, v133
	v_cndmask_b32_e64 v98, 0, v98, s[2:3]
	v_cndmask_b32_e64 v99, 0, v99, s[2:3]
	v_cndmask_b32_e64 v100, 0, v100, s[2:3]
	v_cndmask_b32_e64 v101, 0, v101, s[2:3]
	s_nop 1
	v_mfma_f32_32x32x16_bf16 v[80:95], v[98:101], v[226:229], v[80:95]
	v_mfma_f32_32x32x16_bf16 v[64:79], v[98:101], v[238:241], v[64:79]
	s_ashr_i32 s3, s10, 31
	s_add_u32 s2, s6, s10
	v_lshlrev_b32_e32 v108, 2, v138
	s_addc_u32 s3, s7, s3
	v_ashrrev_i32_e32 v109, 31, v108
	v_lshl_add_u64 v[102:103], s[2:3], 0, v[108:109]
	v_lshlrev_b64 v[98:99], 10, v[102:103]
	v_lshl_add_u64 v[98:99], s[86:87], 0, v[98:99]
	s_lshl_b32 s38, s11, 1
	v_lshl_add_u64 v[100:101], v[98:99], 0, s[38:39]
	v_lshlrev_b32_e32 v98, 1, v107
	v_mov_b32_e32 v99, v97
	v_or_b32_e32 v104, s11, v107
	v_lshl_add_u64 v[110:111], v[100:101], 0, v[98:99]
	v_or_b32_e32 v100, s34, v104
	v_mov_b32_e32 v101, s35
	v_readlane_b32 s16, v254, 50
	v_lshlrev_b64 v[100:101], 2, v[100:101]
	v_readlane_b32 s17, v254, 51
	v_readlane_b32 s18, v254, 52
	v_readlane_b32 s19, v254, 53
	v_readlane_b32 s20, v254, 54
	v_readlane_b32 s21, v254, 55
	v_readlane_b32 s22, v254, 56
	v_readlane_b32 s23, v254, 57
	v_readlane_b32 s24, v254, 58
	v_readlane_b32 s25, v254, 59
	v_readlane_b32 s26, v254, 60
	v_readlane_b32 s27, v254, 61
	v_readlane_b32 s28, v254, 62
	v_readlane_b32 s29, v254, 63
	v_readlane_b32 s30, v255, 0
	v_readlane_b32 s31, v255, 1
	v_lshl_add_u64 v[112:113], s[28:29], 0, v[100:101]
	v_readlane_b32 s16, v253, 34
	v_readlane_b32 s17, v253, 35
	global_load_dword v96, v[112:113], off
	v_bfe_u32 v99, v80, 16, 1
	v_lshl_add_u64 v[112:113], s[16:17], 0, v[100:101]
	global_load_dword v112, v[112:113], off
	v_add3_u32 v80, v80, v99, s48
	global_store_short_d16_hi v[110:111], v80, off
	v_bfe_u32 v80, v81, 16, 1
	v_add3_u32 v80, v81, v80, s48
	global_store_short_d16_hi v[110:111], v80, off offset:1024
	v_bfe_u32 v80, v82, 16, 1
	v_add3_u32 v80, v82, v80, s48
	global_store_short_d16_hi v[110:111], v80, off offset:2048
	v_bfe_u32 v80, v83, 16, 1
	v_add3_u32 v80, v83, v80, s48
	global_store_short_d16_hi v[110:111], v80, off offset:3072
	v_bfe_u32 v80, v84, 16, 1
	v_add3_u32 v82, v84, v80, s48
	v_add_co_u32_e32 v80, vcc, s74, v110
	v_readlane_b32 s18, v253, 36
	s_nop 0
	v_addc_co_u32_e32 v81, vcc, 0, v111, vcc
	global_store_short_d16_hi v[80:81], v82, off
	v_bfe_u32 v82, v85, 16, 1
	v_add3_u32 v82, v85, v82, s48
	global_store_short_d16_hi v[80:81], v82, off offset:1024
	v_bfe_u32 v82, v86, 16, 1
	v_add3_u32 v82, v86, v82, s48
	global_store_short_d16_hi v[80:81], v82, off offset:2048
	v_bfe_u32 v82, v87, 16, 1
	v_add3_u32 v82, v87, v82, s48
	global_store_short_d16_hi v[80:81], v82, off offset:3072
	v_cndmask_b32_e64 v82, 0, 1, s[0:1]
	v_cmp_ne_u32_e64 s[2:3], 1, v82
	s_andn2_b64 vcc, exec, s[0:1]
	v_readlane_b32 s19, v253, 37
	v_readlane_b32 s20, v253, 38
	v_readlane_b32 s21, v253, 39
	v_readlane_b32 s22, v253, 40
	v_readlane_b32 s23, v253, 41
	v_readlane_b32 s24, v253, 42
	v_readlane_b32 s25, v253, 43
	v_readlane_b32 s26, v253, 44
	v_readlane_b32 s27, v253, 45
	v_readlane_b32 s28, v253, 46
	v_readlane_b32 s29, v253, 47
	v_readlane_b32 s30, v253, 48
	v_readlane_b32 s31, v253, 49
	s_cbranch_vccnz .LBB0_904
	v_bfe_u32 v82, v88, 16, 1
	v_add3_u32 v84, v88, v82, s48
	v_add_co_u32_e32 v82, vcc, 0x4000, v110
	s_nop 1
	v_addc_co_u32_e32 v83, vcc, 0, v111, vcc
	global_store_short_d16_hi v[82:83], v84, off
	s_and_b64 vcc, exec, s[2:3]
	s_cbranch_vccz .LBB0_905
